# st0 in-proj/memKV GEMM on v_mfma_f32_16x16x32_bf16 + re-derived EpiP1KV epilogue (LDS-staged full-row bf16 stores, permlane ssq reduce)
# speedup vs baseline: 1.0494x; 1.0040x over previous
.Lst0_fin:
	s_and_b64 vcc, exec, s[78:79]
	v_readlane_b32 s78, v255, 47
	s_waitcnt lgkmcnt(0)
	s_barrier
	s_cbranch_vccnz .LBB0_1363

.LBB0_1262:
	v_add_u32_e32 v8, s11, v158
	v_lshlrev_b32_e32 v168, 1, v128
	v_add_u32_e32 v6, s10, v157
	v_ashrrev_i32_e32 v9, 31, v8
	v_lshl_add_u64 v[10:11], s[2:3], 0, v[168:169]
	v_ashrrev_i32_e32 v7, 31, v6
	v_lshlrev_b64 v[8:9], 11, v[8:9]
	v_lshlrev_b64 v[0:1], 11, v[6:7]
	v_add_u32_e32 v2, 64, v6
	v_add_u32_e32 v4, 0x80, v6
	v_add_u32_e32 v6, 0xc0, v6
	v_lshl_add_u64 v[14:15], v[10:11], 0, v[8:9]
	s_mov_b64 s[0:1], 0xa0000
	v_ashrrev_i32_e32 v3, 31, v2
	v_ashrrev_i32_e32 v5, 31, v4
	v_ashrrev_i32_e32 v7, 31, v6
	v_lshl_add_u64 v[10:11], v[14:15], 0, s[0:1]
	s_xor_b64 s[0:1], s[74:75], -1
	v_lshlrev_b64 v[2:3], 11, v[2:3]
	v_lshlrev_b64 v[4:5], 11, v[4:5]
	v_lshlrev_b64 v[6:7], 11, v[6:7]
	s_andn2_b64 vcc, exec, s[0:1]
	s_mov_b64 s[0:1], 0xe0000
	v_lshl_add_u64 v[0:1], v[132:133], 0, v[0:1]
	v_lshl_add_u64 v[2:3], v[132:133], 0, v[2:3]
	v_lshl_add_u64 v[4:5], v[132:133], 0, v[4:5]
	v_lshl_add_u64 v[6:7], v[132:133], 0, v[6:7]
	v_lshl_add_u64 v[8:9], v[14:15], 0, s[38:39]
	v_lshl_add_u64 v[12:13], v[14:15], 0, s[40:41]
	v_lshl_add_u64 v[14:15], v[14:15], 0, s[0:1]
	s_cbranch_vccnz .LBB0_1264
	s_cmp_lg_u32 16, -1
	v_readfirstlane_b32 s0, v159
	s_cselect_b32 s1, 16, 0
	s_waitcnt vmcnt(63) expcnt(7) lgkmcnt(15)
	s_barrier
	s_add_i32 s0, s0, s1
	s_mov_b32 s1, m0
	s_mov_b32 m0, s0
	s_nop 0
	global_load_lds_dwordx4 v[0:1], off
	s_mov_b32 m0, s1
	s_add_i32 s1, s0, 0x2000
	s_mov_b32 s2, m0
	s_mov_b32 m0, s1
	s_nop 0
	global_load_lds_dwordx4 v[2:3], off
	s_mov_b32 m0, s2
	s_add_i32 s1, s0, 0x4000
	s_mov_b32 s2, m0
	s_mov_b32 m0, s1
	s_nop 0
	global_load_lds_dwordx4 v[4:5], off
	s_mov_b32 m0, s2
	s_add_i32 s1, s0, 0x6000
	s_mov_b32 s2, m0
	s_mov_b32 m0, s1
	s_nop 0
	global_load_lds_dwordx4 v[6:7], off
	s_mov_b32 m0, s2
	s_add_i32 s1, s0, 0x8000
	s_mov_b32 s2, m0
	s_mov_b32 m0, s1
	s_nop 0
	global_load_lds_dwordx4 v[8:9], off
	s_mov_b32 m0, s2
	s_add_i32 s1, s0, 0xa000
	s_mov_b32 s2, m0
	s_mov_b32 m0, s1
	s_nop 0
	global_load_lds_dwordx4 v[10:11], off
	s_mov_b32 m0, s2
	s_add_i32 s1, s0, 0xc000
	s_mov_b32 s2, m0
	s_mov_b32 m0, s1
	s_nop 0
	global_load_lds_dwordx4 v[12:13], off
	s_mov_b32 m0, s2
	s_add_i32 s0, s0, 0xe000
	s_mov_b32 s1, m0
	s_mov_b32 m0, s0
	s_nop 0
	global_load_lds_dwordx4 v[14:15], off
	s_mov_b32 m0, s1
.LBB0_1264:
	v_lshl_add_u64 v[148:149], v[0:1], 0, s[66:67]
	v_mov_b32_e32 v0, 0
	v_lshl_add_u64 v[134:135], v[14:15], 0, s[66:67]
	v_lshl_add_u64 v[136:137], v[12:13], 0, s[66:67]
	v_lshl_add_u64 v[138:139], v[10:11], 0, s[66:67]
	v_lshl_add_u64 v[140:141], v[8:9], 0, s[66:67]
	v_lshl_add_u64 v[142:143], v[6:7], 0, s[66:67]
	v_lshl_add_u64 v[144:145], v[4:5], 0, s[66:67]
	v_lshl_add_u64 v[146:147], v[2:3], 0, s[66:67]
	s_mov_b32 s0, 0
	s_mov_b64 s[2:3], 0
	v_mov_b32_e32 v1, v0
	v_mov_b32_e32 v2, v0
	v_mov_b32_e32 v3, v0
	v_mov_b32_e32 v4, v0
	v_mov_b32_e32 v5, v0
	v_mov_b32_e32 v6, v0
	v_mov_b32_e32 v7, v0
	v_mov_b32_e32 v8, v0
	v_mov_b32_e32 v9, v0
	v_mov_b32_e32 v10, v0
	v_mov_b32_e32 v11, v0
	v_mov_b32_e32 v12, v0
	v_mov_b32_e32 v13, v0
	v_mov_b32_e32 v14, v0
	v_mov_b32_e32 v15, v0
	v_mov_b32_e32 v32, v0
	v_mov_b32_e32 v33, v0
	v_mov_b32_e32 v34, v0
	v_mov_b32_e32 v35, v0
	v_mov_b32_e32 v36, v0
	v_mov_b32_e32 v37, v0
	v_mov_b32_e32 v38, v0
	v_mov_b32_e32 v39, v0
	v_mov_b32_e32 v40, v0
	v_mov_b32_e32 v41, v0
	v_mov_b32_e32 v42, v0
	v_mov_b32_e32 v43, v0
	v_mov_b32_e32 v44, v0
	v_mov_b32_e32 v45, v0
	v_mov_b32_e32 v46, v0
	v_mov_b32_e32 v47, v0
	v_mov_b32_e32 v64, v0
	v_mov_b32_e32 v65, v0
	v_mov_b32_e32 v66, v0
	v_mov_b32_e32 v67, v0
	v_mov_b32_e32 v68, v0
	v_mov_b32_e32 v69, v0
	v_mov_b32_e32 v70, v0
	v_mov_b32_e32 v71, v0
	v_mov_b32_e32 v72, v0
	v_mov_b32_e32 v73, v0
	v_mov_b32_e32 v74, v0
	v_mov_b32_e32 v75, v0
	v_mov_b32_e32 v76, v0
	v_mov_b32_e32 v77, v0
	v_mov_b32_e32 v78, v0
	v_mov_b32_e32 v79, v0
	v_mov_b32_e32 v96, v0
	v_mov_b32_e32 v97, v0
	v_mov_b32_e32 v98, v0
	v_mov_b32_e32 v99, v0
	v_mov_b32_e32 v100, v0
	v_mov_b32_e32 v101, v0
	v_mov_b32_e32 v102, v0
	v_mov_b32_e32 v103, v0
	v_mov_b32_e32 v104, v0
	v_mov_b32_e32 v105, v0
	v_mov_b32_e32 v106, v0
	v_mov_b32_e32 v107, v0
	v_mov_b32_e32 v108, v0
	v_mov_b32_e32 v109, v0
	v_mov_b32_e32 v110, v0
	v_mov_b32_e32 v111, v0
	v_mov_b32_e32 v16, v0
	v_mov_b32_e32 v17, v0
	v_mov_b32_e32 v18, v0
	v_mov_b32_e32 v19, v0
	v_mov_b32_e32 v20, v0
	v_mov_b32_e32 v21, v0
	v_mov_b32_e32 v22, v0
	v_mov_b32_e32 v23, v0
	v_mov_b32_e32 v24, v0
	v_mov_b32_e32 v25, v0
	v_mov_b32_e32 v26, v0
	v_mov_b32_e32 v27, v0
	v_mov_b32_e32 v28, v0
	v_mov_b32_e32 v29, v0
	v_mov_b32_e32 v30, v0
	v_mov_b32_e32 v31, v0
	v_mov_b32_e32 v48, v0
	v_mov_b32_e32 v49, v0
	v_mov_b32_e32 v50, v0
	v_mov_b32_e32 v51, v0
	v_mov_b32_e32 v52, v0
	v_mov_b32_e32 v53, v0
	v_mov_b32_e32 v54, v0
	v_mov_b32_e32 v55, v0
	v_mov_b32_e32 v56, v0
	v_mov_b32_e32 v57, v0
	v_mov_b32_e32 v58, v0
	v_mov_b32_e32 v59, v0
	v_mov_b32_e32 v60, v0
	v_mov_b32_e32 v61, v0
	v_mov_b32_e32 v62, v0
	v_mov_b32_e32 v63, v0
	v_mov_b32_e32 v80, v0
	v_mov_b32_e32 v81, v0
	v_mov_b32_e32 v82, v0
	v_mov_b32_e32 v83, v0
	v_mov_b32_e32 v84, v0
	v_mov_b32_e32 v85, v0
	v_mov_b32_e32 v86, v0
	v_mov_b32_e32 v87, v0
	v_mov_b32_e32 v88, v0
	v_mov_b32_e32 v89, v0
	v_mov_b32_e32 v90, v0
	v_mov_b32_e32 v91, v0
	v_mov_b32_e32 v92, v0
	v_mov_b32_e32 v93, v0
	v_mov_b32_e32 v94, v0
	v_mov_b32_e32 v95, v0
	v_mov_b32_e32 v112, v0
	v_mov_b32_e32 v113, v0
	v_mov_b32_e32 v114, v0
	v_mov_b32_e32 v115, v0
	v_mov_b32_e32 v116, v0
	v_mov_b32_e32 v117, v0
	v_mov_b32_e32 v118, v0
	v_mov_b32_e32 v119, v0
	v_mov_b32_e32 v120, v0
	v_mov_b32_e32 v121, v0
	v_mov_b32_e32 v122, v0
	v_mov_b32_e32 v123, v0
	v_mov_b32_e32 v124, v0
	v_mov_b32_e32 v125, v0
	v_mov_b32_e32 v126, v0
	v_mov_b32_e32 v127, v0
	v_and_b32_e32 v238, 15, v184
	v_bfe_u32 v239, v184, 4, 2
	v_bfe_u32 v240, v184, 1, 3
	v_xor_b32_e32 v239, v239, v240
	v_lshlrev_b32_e32 v239, 4, v239
	v_lshl_add_u32 v239, v238, 7, v239
	v_lshrrev_b32_e32 v240, 8, v184
	v_lshl_add_u32 v236, v240, 14, v239
	v_bfe_u32 v240, v184, 6, 2
	v_lshl_add_u32 v237, v240, 13, v239
	v_add_u32_e32 v237, 0x8000, v237
.LBB0_1265:
	s_add_i32 s1, s0, 0x10000
	s_and_b32 s12, s1, 0x10000
	s_and_b32 s0, s0, 0x10000
	s_add_i32 s0, s0, 16
	v_add_u32_e32 v190, s12, v160
	s_nop 0
	v_readfirstlane_b32 s12, v190
	s_waitcnt vmcnt(0)
	s_barrier
	v_add_u32_e32 v239, s0, v237
	ds_read_b128 v[202:205], v239
	ds_read_b128 v[206:209], v239 offset:2048
	ds_read_b128 v[210:213], v239 offset:4096
	ds_read_b128 v[214:217], v239 offset:6144
	v_add_u32_e32 v238, s0, v236
	ds_read_b128 v[218:221], v238
	ds_read_b128 v[178:181], v238 offset:2048
	ds_read_b128 v[222:225], v238 offset:4096
	ds_read_b128 v[226:229], v238 offset:6144
	v_lshl_add_u64 v[230:231], v[148:149], 0, s[2:3]
	s_mov_b32 m0, s12
	s_nop 0
	global_load_lds_dwordx4 v[230:231], off
	s_waitcnt lgkmcnt(3)
	v_mfma_f32_16x16x32_bf16 v[0:3], v[202:205], v[218:221], v[0:3]
	v_mfma_f32_16x16x32_bf16 v[32:35], v[206:209], v[218:221], v[32:35]
	v_lshl_add_u64 v[230:231], v[146:147], 0, s[2:3]
	s_add_i32 s13, s12, 0x2000
	s_mov_b32 m0, s13
	s_nop 0
	global_load_lds_dwordx4 v[230:231], off
	v_mfma_f32_16x16x32_bf16 v[64:67], v[210:213], v[218:221], v[64:67]
	v_mfma_f32_16x16x32_bf16 v[96:99], v[214:217], v[218:221], v[96:99]
	s_waitcnt lgkmcnt(2)
	v_mfma_f32_16x16x32_bf16 v[4:7], v[202:205], v[178:181], v[4:7]
	v_mfma_f32_16x16x32_bf16 v[36:39], v[206:209], v[178:181], v[36:39]
	v_lshl_add_u64 v[230:231], v[144:145], 0, s[2:3]
	s_add_i32 s13, s12, 0x4000
	s_mov_b32 m0, s13
	s_nop 0
	global_load_lds_dwordx4 v[230:231], off
	v_mfma_f32_16x16x32_bf16 v[68:71], v[210:213], v[178:181], v[68:71]
	v_mfma_f32_16x16x32_bf16 v[100:103], v[214:217], v[178:181], v[100:103]
	s_waitcnt lgkmcnt(1)
	v_mfma_f32_16x16x32_bf16 v[8:11], v[202:205], v[222:225], v[8:11]
	v_mfma_f32_16x16x32_bf16 v[40:43], v[206:209], v[222:225], v[40:43]
	v_lshl_add_u64 v[230:231], v[142:143], 0, s[2:3]
	s_add_i32 s13, s12, 0x6000
	s_mov_b32 m0, s13
	s_nop 0
	global_load_lds_dwordx4 v[230:231], off
	v_mfma_f32_16x16x32_bf16 v[72:75], v[210:213], v[222:225], v[72:75]
	v_mfma_f32_16x16x32_bf16 v[104:107], v[214:217], v[222:225], v[104:107]
	s_waitcnt lgkmcnt(0)
	v_mfma_f32_16x16x32_bf16 v[12:15], v[202:205], v[226:229], v[12:15]
	v_mfma_f32_16x16x32_bf16 v[44:47], v[206:209], v[226:229], v[44:47]
	v_lshl_add_u64 v[230:231], v[140:141], 0, s[2:3]
	s_add_i32 s13, s12, 0x8000
	s_mov_b32 m0, s13
	s_nop 0
	global_load_lds_dwordx4 v[230:231], off
	v_mfma_f32_16x16x32_bf16 v[76:79], v[210:213], v[226:229], v[76:79]
	v_mfma_f32_16x16x32_bf16 v[108:111], v[214:217], v[226:229], v[108:111]
	ds_read_b128 v[218:221], v238 offset:8192
	ds_read_b128 v[178:181], v238 offset:10240
	ds_read_b128 v[222:225], v238 offset:12288
	ds_read_b128 v[226:229], v238 offset:14336
	s_waitcnt lgkmcnt(3)
	v_mfma_f32_16x16x32_bf16 v[16:19], v[202:205], v[218:221], v[16:19]
	v_mfma_f32_16x16x32_bf16 v[48:51], v[206:209], v[218:221], v[48:51]
	v_lshl_add_u64 v[230:231], v[138:139], 0, s[2:3]
	s_add_i32 s13, s12, 0xa000
	s_mov_b32 m0, s13
	s_nop 0
	global_load_lds_dwordx4 v[230:231], off
	v_mfma_f32_16x16x32_bf16 v[80:83], v[210:213], v[218:221], v[80:83]
	v_mfma_f32_16x16x32_bf16 v[112:115], v[214:217], v[218:221], v[112:115]
	s_waitcnt lgkmcnt(2)
	v_mfma_f32_16x16x32_bf16 v[20:23], v[202:205], v[178:181], v[20:23]
	v_mfma_f32_16x16x32_bf16 v[52:55], v[206:209], v[178:181], v[52:55]
	v_lshl_add_u64 v[230:231], v[136:137], 0, s[2:3]
	s_add_i32 s13, s12, 0xc000
	s_mov_b32 m0, s13
	s_nop 0
	global_load_lds_dwordx4 v[230:231], off
	v_mfma_f32_16x16x32_bf16 v[84:87], v[210:213], v[178:181], v[84:87]
	v_mfma_f32_16x16x32_bf16 v[116:119], v[214:217], v[178:181], v[116:119]
	s_waitcnt lgkmcnt(1)
	v_mfma_f32_16x16x32_bf16 v[24:27], v[202:205], v[222:225], v[24:27]
	v_mfma_f32_16x16x32_bf16 v[56:59], v[206:209], v[222:225], v[56:59]
	v_lshl_add_u64 v[230:231], v[134:135], 0, s[2:3]
	s_add_i32 s13, s12, 0xe000
	s_mov_b32 m0, s13
	s_nop 0
	global_load_lds_dwordx4 v[230:231], off
	s_add_u32 s2, s2, 0x80
	s_addc_u32 s3, s3, 0
	s_cmpk_eq_i32 s2, 0x780
	v_mfma_f32_16x16x32_bf16 v[88:91], v[210:213], v[222:225], v[88:91]
	v_mfma_f32_16x16x32_bf16 v[120:123], v[214:217], v[222:225], v[120:123]
	s_waitcnt lgkmcnt(0)
	v_mfma_f32_16x16x32_bf16 v[28:31], v[202:205], v[226:229], v[28:31]
	v_mfma_f32_16x16x32_bf16 v[60:63], v[206:209], v[226:229], v[60:63]
	v_mfma_f32_16x16x32_bf16 v[92:95], v[210:213], v[226:229], v[92:95]
	v_mfma_f32_16x16x32_bf16 v[124:127], v[214:217], v[226:229], v[124:127]
	v_xor_b32_e32 v239, 64, v237
	v_add_u32_e32 v239, s0, v239
	ds_read_b128 v[202:205], v239
	ds_read_b128 v[206:209], v239 offset:2048
	ds_read_b128 v[210:213], v239 offset:4096
	ds_read_b128 v[214:217], v239 offset:6144
	v_xor_b32_e32 v238, 64, v236
	v_add_u32_e32 v238, s0, v238
	ds_read_b128 v[218:221], v238
	ds_read_b128 v[178:181], v238 offset:2048
	ds_read_b128 v[222:225], v238 offset:4096
	ds_read_b128 v[226:229], v238 offset:6144
	s_waitcnt lgkmcnt(3)
	v_mfma_f32_16x16x32_bf16 v[0:3], v[202:205], v[218:221], v[0:3]
	v_mfma_f32_16x16x32_bf16 v[32:35], v[206:209], v[218:221], v[32:35]
	v_mfma_f32_16x16x32_bf16 v[64:67], v[210:213], v[218:221], v[64:67]
	v_mfma_f32_16x16x32_bf16 v[96:99], v[214:217], v[218:221], v[96:99]
	s_waitcnt lgkmcnt(2)
	v_mfma_f32_16x16x32_bf16 v[4:7], v[202:205], v[178:181], v[4:7]
	v_mfma_f32_16x16x32_bf16 v[36:39], v[206:209], v[178:181], v[36:39]
	v_mfma_f32_16x16x32_bf16 v[68:71], v[210:213], v[178:181], v[68:71]
	v_mfma_f32_16x16x32_bf16 v[100:103], v[214:217], v[178:181], v[100:103]
	s_waitcnt lgkmcnt(1)
	v_mfma_f32_16x16x32_bf16 v[8:11], v[202:205], v[222:225], v[8:11]
	v_mfma_f32_16x16x32_bf16 v[40:43], v[206:209], v[222:225], v[40:43]
	v_mfma_f32_16x16x32_bf16 v[72:75], v[210:213], v[222:225], v[72:75]
	v_mfma_f32_16x16x32_bf16 v[104:107], v[214:217], v[222:225], v[104:107]
	s_waitcnt lgkmcnt(0)
	v_mfma_f32_16x16x32_bf16 v[12:15], v[202:205], v[226:229], v[12:15]
	v_mfma_f32_16x16x32_bf16 v[44:47], v[206:209], v[226:229], v[44:47]
	v_mfma_f32_16x16x32_bf16 v[76:79], v[210:213], v[226:229], v[76:79]
	v_mfma_f32_16x16x32_bf16 v[108:111], v[214:217], v[226:229], v[108:111]
	ds_read_b128 v[218:221], v238 offset:8192
	ds_read_b128 v[178:181], v238 offset:10240
	ds_read_b128 v[222:225], v238 offset:12288
	ds_read_b128 v[226:229], v238 offset:14336
	s_waitcnt lgkmcnt(3)
	v_mfma_f32_16x16x32_bf16 v[16:19], v[202:205], v[218:221], v[16:19]
	v_mfma_f32_16x16x32_bf16 v[48:51], v[206:209], v[218:221], v[48:51]
	v_mfma_f32_16x16x32_bf16 v[80:83], v[210:213], v[218:221], v[80:83]
	v_mfma_f32_16x16x32_bf16 v[112:115], v[214:217], v[218:221], v[112:115]
	s_waitcnt lgkmcnt(2)
	v_mfma_f32_16x16x32_bf16 v[20:23], v[202:205], v[178:181], v[20:23]
	v_mfma_f32_16x16x32_bf16 v[52:55], v[206:209], v[178:181], v[52:55]
	v_mfma_f32_16x16x32_bf16 v[84:87], v[210:213], v[178:181], v[84:87]
	v_mfma_f32_16x16x32_bf16 v[116:119], v[214:217], v[178:181], v[116:119]
	s_waitcnt lgkmcnt(1)
	v_mfma_f32_16x16x32_bf16 v[24:27], v[202:205], v[222:225], v[24:27]
	v_mfma_f32_16x16x32_bf16 v[56:59], v[206:209], v[222:225], v[56:59]
	v_mfma_f32_16x16x32_bf16 v[88:91], v[210:213], v[222:225], v[88:91]
	v_mfma_f32_16x16x32_bf16 v[120:123], v[214:217], v[222:225], v[120:123]
	s_waitcnt lgkmcnt(0)
	v_mfma_f32_16x16x32_bf16 v[28:31], v[202:205], v[226:229], v[28:31]
	v_mfma_f32_16x16x32_bf16 v[60:63], v[206:209], v[226:229], v[60:63]
	v_mfma_f32_16x16x32_bf16 v[92:95], v[210:213], v[226:229], v[92:95]
	v_mfma_f32_16x16x32_bf16 v[124:127], v[214:217], v[226:229], v[124:127]
	s_mov_b32 s0, s1
	s_cbranch_scc0 .LBB0_1265
	s_waitcnt vmcnt(0)
	s_barrier
	v_mov_b32_e32 v134, 0x358637bd
	s_and_saveexec_b64 s[2:3], s[6:7]
	s_cbranch_execz .LBB0_1268
	v_add_u32_e32 v134, s10, v129
	v_ashrrev_i32_e32 v135, 31, v134
	v_lshlrev_b64 v[134:135], 6, v[134:135]
	v_lshl_add_u64 v[146:147], s[72:73], 0, v[134:135]
	global_load_dwordx4 v[134:137], v[146:147], off
	global_load_dwordx4 v[138:141], v[146:147], off offset:16
	global_load_dwordx4 v[142:145], v[146:147], off offset:32
	s_nop 0
	global_load_dwordx4 v[146:149], v[146:147], off offset:48
	s_waitcnt vmcnt(3)
	v_mov_b32_e32 v178, v135
	v_mov_b32_e32 v179, v136
	v_mov_b32_e32 v135, v137
	v_pk_add_f32 v[134:135], v[178:179], v[134:135]
	s_waitcnt vmcnt(2)
	v_mov_b32_e32 v180, v139
	v_mov_b32_e32 v181, v140
	v_mov_b32_e32 v139, v141
	v_add_f32_e32 v134, 0, v134
	v_pk_add_f32 v[136:137], v[180:181], v[138:139]
	v_add_f32_e32 v134, v134, v135
	s_waitcnt vmcnt(1)
	v_mov_b32_e32 v182, v143
	v_mov_b32_e32 v183, v144
	v_mov_b32_e32 v143, v145
	v_add_f32_e32 v134, v134, v136
	v_pk_add_f32 v[138:139], v[182:183], v[142:143]
	v_add_f32_e32 v134, v134, v137
	s_waitcnt vmcnt(0)
	v_mov_b32_e32 v202, v147
	v_mov_b32_e32 v203, v148
	v_mov_b32_e32 v147, v149
	v_add_f32_e32 v134, v134, v138
	v_add_f32_e32 v136, v134, v139
	v_pk_add_f32 v[134:135], v[202:203], v[146:147]
	s_nop 0
	v_add_f32_e32 v134, v136, v134
	v_add_f32_e32 v134, v134, v135
	v_fmamk_f32 v134, v134, 0x3a800000, v187

.LBB0_1270:
	v_add_u32_e32 v239, 0x10010, v237
	ds_read_b128 v[202:205], v239
	ds_read_b128 v[206:209], v239 offset:2048
	ds_read_b128 v[210:213], v239 offset:4096
	ds_read_b128 v[214:217], v239 offset:6144
	v_add_u32_e32 v238, 0x10010, v236
	ds_read_b128 v[218:221], v238
	ds_read_b128 v[178:181], v238 offset:2048
	ds_read_b128 v[222:225], v238 offset:4096
	ds_read_b128 v[226:229], v238 offset:6144
	s_waitcnt lgkmcnt(3)
	v_mfma_f32_16x16x32_bf16 v[0:3], v[202:205], v[218:221], v[0:3]
	v_mfma_f32_16x16x32_bf16 v[32:35], v[206:209], v[218:221], v[32:35]
	v_mfma_f32_16x16x32_bf16 v[64:67], v[210:213], v[218:221], v[64:67]
	v_mfma_f32_16x16x32_bf16 v[96:99], v[214:217], v[218:221], v[96:99]
	s_waitcnt lgkmcnt(2)
	v_mfma_f32_16x16x32_bf16 v[4:7], v[202:205], v[178:181], v[4:7]
	v_mfma_f32_16x16x32_bf16 v[36:39], v[206:209], v[178:181], v[36:39]
	v_mfma_f32_16x16x32_bf16 v[68:71], v[210:213], v[178:181], v[68:71]
	v_mfma_f32_16x16x32_bf16 v[100:103], v[214:217], v[178:181], v[100:103]
	s_waitcnt lgkmcnt(1)
	v_mfma_f32_16x16x32_bf16 v[8:11], v[202:205], v[222:225], v[8:11]
	v_mfma_f32_16x16x32_bf16 v[40:43], v[206:209], v[222:225], v[40:43]
	v_mfma_f32_16x16x32_bf16 v[72:75], v[210:213], v[222:225], v[72:75]
	v_mfma_f32_16x16x32_bf16 v[104:107], v[214:217], v[222:225], v[104:107]
	s_waitcnt lgkmcnt(0)
	v_mfma_f32_16x16x32_bf16 v[12:15], v[202:205], v[226:229], v[12:15]
	v_mfma_f32_16x16x32_bf16 v[44:47], v[206:209], v[226:229], v[44:47]
	v_mfma_f32_16x16x32_bf16 v[76:79], v[210:213], v[226:229], v[76:79]
	v_mfma_f32_16x16x32_bf16 v[108:111], v[214:217], v[226:229], v[108:111]
	ds_read_b128 v[218:221], v238 offset:8192
	ds_read_b128 v[178:181], v238 offset:10240
	ds_read_b128 v[222:225], v238 offset:12288
	ds_read_b128 v[226:229], v238 offset:14336
	s_waitcnt lgkmcnt(3)
	v_mfma_f32_16x16x32_bf16 v[16:19], v[202:205], v[218:221], v[16:19]
	v_mfma_f32_16x16x32_bf16 v[48:51], v[206:209], v[218:221], v[48:51]
	v_mfma_f32_16x16x32_bf16 v[80:83], v[210:213], v[218:221], v[80:83]
	v_mfma_f32_16x16x32_bf16 v[112:115], v[214:217], v[218:221], v[112:115]
	s_waitcnt lgkmcnt(2)
	v_mfma_f32_16x16x32_bf16 v[20:23], v[202:205], v[178:181], v[20:23]
	v_mfma_f32_16x16x32_bf16 v[52:55], v[206:209], v[178:181], v[52:55]
	v_mfma_f32_16x16x32_bf16 v[84:87], v[210:213], v[178:181], v[84:87]
	v_mfma_f32_16x16x32_bf16 v[116:119], v[214:217], v[178:181], v[116:119]
	s_waitcnt lgkmcnt(1)
	v_mfma_f32_16x16x32_bf16 v[24:27], v[202:205], v[222:225], v[24:27]
	v_mfma_f32_16x16x32_bf16 v[56:59], v[206:209], v[222:225], v[56:59]
	v_mfma_f32_16x16x32_bf16 v[88:91], v[210:213], v[222:225], v[88:91]
	v_mfma_f32_16x16x32_bf16 v[120:123], v[214:217], v[222:225], v[120:123]
	s_waitcnt lgkmcnt(0)
	v_mfma_f32_16x16x32_bf16 v[28:31], v[202:205], v[226:229], v[28:31]
	v_mfma_f32_16x16x32_bf16 v[60:63], v[206:209], v[226:229], v[60:63]
	v_mfma_f32_16x16x32_bf16 v[92:95], v[210:213], v[226:229], v[92:95]
	v_mfma_f32_16x16x32_bf16 v[124:127], v[214:217], v[226:229], v[124:127]
	v_xor_b32_e32 v239, 64, v237
	v_add_u32_e32 v239, 0x10010, v239
	ds_read_b128 v[202:205], v239
	ds_read_b128 v[206:209], v239 offset:2048
	ds_read_b128 v[210:213], v239 offset:4096
	ds_read_b128 v[214:217], v239 offset:6144
	v_xor_b32_e32 v238, 64, v236
	v_add_u32_e32 v238, 0x10010, v238
	ds_read_b128 v[218:221], v238
	ds_read_b128 v[178:181], v238 offset:2048
	ds_read_b128 v[222:225], v238 offset:4096
	ds_read_b128 v[226:229], v238 offset:6144
	s_waitcnt lgkmcnt(3)
	v_mfma_f32_16x16x32_bf16 v[0:3], v[202:205], v[218:221], v[0:3]
	v_mfma_f32_16x16x32_bf16 v[32:35], v[206:209], v[218:221], v[32:35]
	v_mfma_f32_16x16x32_bf16 v[64:67], v[210:213], v[218:221], v[64:67]
	v_mfma_f32_16x16x32_bf16 v[96:99], v[214:217], v[218:221], v[96:99]
	s_waitcnt lgkmcnt(2)
	v_mfma_f32_16x16x32_bf16 v[4:7], v[202:205], v[178:181], v[4:7]
	v_mfma_f32_16x16x32_bf16 v[36:39], v[206:209], v[178:181], v[36:39]
	v_mfma_f32_16x16x32_bf16 v[68:71], v[210:213], v[178:181], v[68:71]
	v_mfma_f32_16x16x32_bf16 v[100:103], v[214:217], v[178:181], v[100:103]
	s_waitcnt lgkmcnt(1)
	v_mfma_f32_16x16x32_bf16 v[8:11], v[202:205], v[222:225], v[8:11]
	v_mfma_f32_16x16x32_bf16 v[40:43], v[206:209], v[222:225], v[40:43]
	v_mfma_f32_16x16x32_bf16 v[72:75], v[210:213], v[222:225], v[72:75]
	v_mfma_f32_16x16x32_bf16 v[104:107], v[214:217], v[222:225], v[104:107]
	s_waitcnt lgkmcnt(0)
	v_mfma_f32_16x16x32_bf16 v[12:15], v[202:205], v[226:229], v[12:15]
	v_mfma_f32_16x16x32_bf16 v[44:47], v[206:209], v[226:229], v[44:47]
	v_mfma_f32_16x16x32_bf16 v[76:79], v[210:213], v[226:229], v[76:79]
	v_mfma_f32_16x16x32_bf16 v[108:111], v[214:217], v[226:229], v[108:111]
	ds_read_b128 v[218:221], v238 offset:8192
	ds_read_b128 v[178:181], v238 offset:10240
	ds_read_b128 v[222:225], v238 offset:12288
	ds_read_b128 v[226:229], v238 offset:14336
	s_waitcnt lgkmcnt(3)
	v_mfma_f32_16x16x32_bf16 v[16:19], v[202:205], v[218:221], v[16:19]
	v_mfma_f32_16x16x32_bf16 v[48:51], v[206:209], v[218:221], v[48:51]
	v_mfma_f32_16x16x32_bf16 v[80:83], v[210:213], v[218:221], v[80:83]
	v_mfma_f32_16x16x32_bf16 v[112:115], v[214:217], v[218:221], v[112:115]
	s_waitcnt lgkmcnt(2)
	v_mfma_f32_16x16x32_bf16 v[20:23], v[202:205], v[178:181], v[20:23]
	v_mfma_f32_16x16x32_bf16 v[52:55], v[206:209], v[178:181], v[52:55]
	v_mfma_f32_16x16x32_bf16 v[84:87], v[210:213], v[178:181], v[84:87]
	v_mfma_f32_16x16x32_bf16 v[116:119], v[214:217], v[178:181], v[116:119]
	s_waitcnt lgkmcnt(1)
	v_mfma_f32_16x16x32_bf16 v[24:27], v[202:205], v[222:225], v[24:27]
	v_mfma_f32_16x16x32_bf16 v[56:59], v[206:209], v[222:225], v[56:59]
	v_mfma_f32_16x16x32_bf16 v[88:91], v[210:213], v[222:225], v[88:91]
	v_mfma_f32_16x16x32_bf16 v[120:123], v[214:217], v[222:225], v[120:123]
	s_waitcnt lgkmcnt(0)
	v_mfma_f32_16x16x32_bf16 v[28:31], v[202:205], v[226:229], v[28:31]
	v_mfma_f32_16x16x32_bf16 v[60:63], v[206:209], v[226:229], v[60:63]
	v_mfma_f32_16x16x32_bf16 v[92:95], v[210:213], v[226:229], v[92:95]
	v_mfma_f32_16x16x32_bf16 v[124:127], v[214:217], v[226:229], v[124:127]
	s_and_saveexec_b64 s[2:3], s[6:7]
	s_cbranch_execz .LBB0_1272
	v_mul_f32_e32 v135, 0x4b800000, v134
	v_cmp_gt_f32_e32 vcc, s28, v134
	s_nop 1
	v_cndmask_b32_e32 v134, v134, v135, vcc
	v_rsq_f32_e32 v134, v134
	s_nop 0
	v_mul_f32_e32 v135, 0x45800000, v134
	v_cndmask_b32_e32 v134, v134, v135, vcc
	ds_write_b32 v161, v134
.LBB0_1272:
	s_or_b64 exec, exec, s[2:3]
	s_waitcnt lgkmcnt(0)
	s_barrier
	v_and_b32_e32 v134, 15, v129
	v_bfe_u32 v135, v129, 4, 2
	v_lshrrev_b32_e32 v136, 6, v129
	v_lshrrev_b32_e32 v137, 8, v129
	v_and_b32_e32 v138, 3, v136
	v_lshl_add_u32 v139, v137, 7, v134
	v_add_u32_e32 v142, s10, v139
	v_lshlrev_b32_e32 v140, 2, v139
	v_add_u32_e32 v140, 0x20010, v140
	ds_read2_b32 v[202:203], v140 offset0:0 offset1:16
	ds_read2_b32 v[204:205], v140 offset0:32 offset1:48
	ds_read2_b32 v[206:207], v140 offset0:64 offset1:80
	ds_read2_b32 v[208:209], v140 offset0:96 offset1:112
	v_lshlrev_b32_e32 v141, 6, v138
	v_add_u32_e32 v141, s11, v141
	v_and_b32_e32 v139, 63, v129
	v_readfirstlane_b32 s18, v141
	v_cmp_gt_u32_e64 s[14:15], 16, v139
	s_nop 7
	s_waitcnt lgkmcnt(0)
	v_mul_f32_e32 v0, v0, v202
	v_mul_f32_e32 v1, v1, v202
	v_mul_f32_e32 v2, v2, v202
	v_mul_f32_e32 v3, v3, v202
	v_mul_f32_e32 v32, v32, v202
	v_mul_f32_e32 v33, v33, v202
	v_mul_f32_e32 v34, v34, v202
	v_mul_f32_e32 v35, v35, v202
	v_mul_f32_e32 v64, v64, v202
	v_mul_f32_e32 v65, v65, v202
	v_mul_f32_e32 v66, v66, v202
	v_mul_f32_e32 v67, v67, v202
	v_mul_f32_e32 v96, v96, v202
	v_mul_f32_e32 v97, v97, v202
	v_mul_f32_e32 v98, v98, v202
	v_mul_f32_e32 v99, v99, v202
	v_mul_f32_e32 v4, v4, v203
	v_mul_f32_e32 v5, v5, v203
	v_mul_f32_e32 v6, v6, v203
	v_mul_f32_e32 v7, v7, v203
	v_mul_f32_e32 v36, v36, v203
	v_mul_f32_e32 v37, v37, v203
	v_mul_f32_e32 v38, v38, v203
	v_mul_f32_e32 v39, v39, v203
	v_mul_f32_e32 v68, v68, v203
	v_mul_f32_e32 v69, v69, v203
	v_mul_f32_e32 v70, v70, v203
	v_mul_f32_e32 v71, v71, v203
	v_mul_f32_e32 v100, v100, v203
	v_mul_f32_e32 v101, v101, v203
	v_mul_f32_e32 v102, v102, v203
	v_mul_f32_e32 v103, v103, v203
	v_mul_f32_e32 v8, v8, v204
	v_mul_f32_e32 v9, v9, v204
	v_mul_f32_e32 v10, v10, v204
	v_mul_f32_e32 v11, v11, v204
	v_mul_f32_e32 v40, v40, v204
	v_mul_f32_e32 v41, v41, v204
	v_mul_f32_e32 v42, v42, v204
	v_mul_f32_e32 v43, v43, v204
	v_mul_f32_e32 v72, v72, v204
	v_mul_f32_e32 v73, v73, v204
	v_mul_f32_e32 v74, v74, v204
	v_mul_f32_e32 v75, v75, v204
	v_mul_f32_e32 v104, v104, v204
	v_mul_f32_e32 v105, v105, v204
	v_mul_f32_e32 v106, v106, v204
	v_mul_f32_e32 v107, v107, v204
	v_mul_f32_e32 v12, v12, v205
	v_mul_f32_e32 v13, v13, v205
	v_mul_f32_e32 v14, v14, v205
	v_mul_f32_e32 v15, v15, v205
	v_mul_f32_e32 v44, v44, v205
	v_mul_f32_e32 v45, v45, v205
	v_mul_f32_e32 v46, v46, v205
	v_mul_f32_e32 v47, v47, v205
	v_mul_f32_e32 v76, v76, v205
	v_mul_f32_e32 v77, v77, v205
	v_mul_f32_e32 v78, v78, v205
	v_mul_f32_e32 v79, v79, v205
	v_mul_f32_e32 v108, v108, v205
	v_mul_f32_e32 v109, v109, v205
	v_mul_f32_e32 v110, v110, v205
	v_mul_f32_e32 v111, v111, v205
	v_mul_f32_e32 v16, v16, v206
	v_mul_f32_e32 v17, v17, v206
	v_mul_f32_e32 v18, v18, v206
	v_mul_f32_e32 v19, v19, v206
	v_mul_f32_e32 v48, v48, v206
	v_mul_f32_e32 v49, v49, v206
	v_mul_f32_e32 v50, v50, v206
	v_mul_f32_e32 v51, v51, v206
	v_mul_f32_e32 v80, v80, v206
	v_mul_f32_e32 v81, v81, v206
	v_mul_f32_e32 v82, v82, v206
	v_mul_f32_e32 v83, v83, v206
	v_mul_f32_e32 v112, v112, v206
	v_mul_f32_e32 v113, v113, v206
	v_mul_f32_e32 v114, v114, v206
	v_mul_f32_e32 v115, v115, v206
	v_mul_f32_e32 v20, v20, v207
	v_mul_f32_e32 v21, v21, v207
	v_mul_f32_e32 v22, v22, v207
	v_mul_f32_e32 v23, v23, v207
	v_mul_f32_e32 v52, v52, v207
	v_mul_f32_e32 v53, v53, v207
	v_mul_f32_e32 v54, v54, v207
	v_mul_f32_e32 v55, v55, v207
	v_mul_f32_e32 v84, v84, v207
	v_mul_f32_e32 v85, v85, v207
	v_mul_f32_e32 v86, v86, v207
	v_mul_f32_e32 v87, v87, v207
	v_mul_f32_e32 v116, v116, v207
	v_mul_f32_e32 v117, v117, v207
	v_mul_f32_e32 v118, v118, v207
	v_mul_f32_e32 v119, v119, v207
	v_mul_f32_e32 v24, v24, v208
	v_mul_f32_e32 v25, v25, v208
	v_mul_f32_e32 v26, v26, v208
	v_mul_f32_e32 v27, v27, v208
	v_mul_f32_e32 v56, v56, v208
	v_mul_f32_e32 v57, v57, v208
	v_mul_f32_e32 v58, v58, v208
	v_mul_f32_e32 v59, v59, v208
	v_mul_f32_e32 v88, v88, v208
	v_mul_f32_e32 v89, v89, v208
	v_mul_f32_e32 v90, v90, v208
	v_mul_f32_e32 v91, v91, v208
	v_mul_f32_e32 v120, v120, v208
	v_mul_f32_e32 v121, v121, v208
	v_mul_f32_e32 v122, v122, v208
	v_mul_f32_e32 v123, v123, v208
	v_mul_f32_e32 v28, v28, v209
	v_mul_f32_e32 v29, v29, v209
	v_mul_f32_e32 v30, v30, v209
	v_mul_f32_e32 v31, v31, v209
	v_mul_f32_e32 v60, v60, v209
	v_mul_f32_e32 v61, v61, v209
	v_mul_f32_e32 v62, v62, v209
	v_mul_f32_e32 v63, v63, v209
	v_mul_f32_e32 v92, v92, v209
	v_mul_f32_e32 v93, v93, v209
	v_mul_f32_e32 v94, v94, v209
	v_mul_f32_e32 v95, v95, v209
	v_mul_f32_e32 v124, v124, v209
	v_mul_f32_e32 v125, v125, v209
	v_mul_f32_e32 v126, v126, v209
	v_mul_f32_e32 v127, v127, v209
	s_cmp_gt_i32 s10, 0x3fff
	s_cbranch_scc1 .Lst0_mem
	s_cmpk_ge_i32 s18, 0x180
	s_cbranch_scc1 .Lst0_nossq
	v_mul_f32_e32 v139, v0, v0
	v_fmac_f32_e32 v139, v1, v1
	v_mul_f32_e32 v140, v2, v2
	v_fmac_f32_e32 v140, v3, v3
	v_add_f32_e32 v139, v139, v140
	v_mov_b32_e32 v210, v139
	v_mul_f32_e32 v139, v32, v32
	v_fmac_f32_e32 v139, v33, v33
	v_mul_f32_e32 v140, v34, v34
	v_fmac_f32_e32 v140, v35, v35
	v_add_f32_e32 v139, v139, v140
	v_add_f32_e32 v210, v210, v139
	v_mul_f32_e32 v139, v64, v64
	v_fmac_f32_e32 v139, v65, v65
	v_mul_f32_e32 v140, v66, v66
	v_fmac_f32_e32 v140, v67, v67
	v_add_f32_e32 v139, v139, v140
	v_add_f32_e32 v210, v210, v139
	v_mul_f32_e32 v139, v96, v96
	v_fmac_f32_e32 v139, v97, v97
	v_mul_f32_e32 v140, v98, v98
	v_fmac_f32_e32 v140, v99, v99
	v_add_f32_e32 v139, v139, v140
	v_add_f32_e32 v210, v210, v139
	v_mov_b32_e32 v139, v210
	v_mov_b32_e32 v140, v210
	s_nop 1
	v_permlane16_swap_b32_e32 v139, v140
	v_add_f32_e32 v210, v139, v140
	v_mov_b32_e32 v139, v210
	v_mov_b32_e32 v140, v210
	s_nop 1
	v_permlane32_swap_b32_e32 v139, v140
	v_add_f32_e32 v210, v139, v140
	v_mul_f32_e32 v139, v4, v4
	v_fmac_f32_e32 v139, v5, v5
	v_mul_f32_e32 v140, v6, v6
	v_fmac_f32_e32 v140, v7, v7
	v_add_f32_e32 v139, v139, v140
	v_mov_b32_e32 v211, v139
	v_mul_f32_e32 v139, v36, v36
	v_fmac_f32_e32 v139, v37, v37
	v_mul_f32_e32 v140, v38, v38
	v_fmac_f32_e32 v140, v39, v39
	v_add_f32_e32 v139, v139, v140
	v_add_f32_e32 v211, v211, v139
	v_mul_f32_e32 v139, v68, v68
	v_fmac_f32_e32 v139, v69, v69
	v_mul_f32_e32 v140, v70, v70
	v_fmac_f32_e32 v140, v71, v71
	v_add_f32_e32 v139, v139, v140
	v_add_f32_e32 v211, v211, v139
	v_mul_f32_e32 v139, v100, v100
	v_fmac_f32_e32 v139, v101, v101
	v_mul_f32_e32 v140, v102, v102
	v_fmac_f32_e32 v140, v103, v103
	v_add_f32_e32 v139, v139, v140
	v_add_f32_e32 v211, v211, v139
	v_mov_b32_e32 v139, v211
	v_mov_b32_e32 v140, v211
	s_nop 1
	v_permlane16_swap_b32_e32 v139, v140
	v_add_f32_e32 v211, v139, v140
	v_mov_b32_e32 v139, v211
	v_mov_b32_e32 v140, v211
	s_nop 1
	v_permlane32_swap_b32_e32 v139, v140
	v_add_f32_e32 v211, v139, v140
	v_mul_f32_e32 v139, v8, v8
	v_fmac_f32_e32 v139, v9, v9
	v_mul_f32_e32 v140, v10, v10
	v_fmac_f32_e32 v140, v11, v11
	v_add_f32_e32 v139, v139, v140
	v_mov_b32_e32 v212, v139
	v_mul_f32_e32 v139, v40, v40
	v_fmac_f32_e32 v139, v41, v41
	v_mul_f32_e32 v140, v42, v42
	v_fmac_f32_e32 v140, v43, v43
	v_add_f32_e32 v139, v139, v140
	v_add_f32_e32 v212, v212, v139
	v_mul_f32_e32 v139, v72, v72
	v_fmac_f32_e32 v139, v73, v73
	v_mul_f32_e32 v140, v74, v74
	v_fmac_f32_e32 v140, v75, v75
	v_add_f32_e32 v139, v139, v140
	v_add_f32_e32 v212, v212, v139
	v_mul_f32_e32 v139, v104, v104
	v_fmac_f32_e32 v139, v105, v105
	v_mul_f32_e32 v140, v106, v106
	v_fmac_f32_e32 v140, v107, v107
	v_add_f32_e32 v139, v139, v140
	v_add_f32_e32 v212, v212, v139
	v_mov_b32_e32 v139, v212
	v_mov_b32_e32 v140, v212
	s_nop 1
	v_permlane16_swap_b32_e32 v139, v140
	v_add_f32_e32 v212, v139, v140
	v_mov_b32_e32 v139, v212
	v_mov_b32_e32 v140, v212
	s_nop 1
	v_permlane32_swap_b32_e32 v139, v140
	v_add_f32_e32 v212, v139, v140
	v_mul_f32_e32 v139, v12, v12
	v_fmac_f32_e32 v139, v13, v13
	v_mul_f32_e32 v140, v14, v14
	v_fmac_f32_e32 v140, v15, v15
	v_add_f32_e32 v139, v139, v140
	v_mov_b32_e32 v213, v139
	v_mul_f32_e32 v139, v44, v44
	v_fmac_f32_e32 v139, v45, v45
	v_mul_f32_e32 v140, v46, v46
	v_fmac_f32_e32 v140, v47, v47
	v_add_f32_e32 v139, v139, v140
	v_add_f32_e32 v213, v213, v139
	v_mul_f32_e32 v139, v76, v76
	v_fmac_f32_e32 v139, v77, v77
	v_mul_f32_e32 v140, v78, v78
	v_fmac_f32_e32 v140, v79, v79
	v_add_f32_e32 v139, v139, v140
	v_add_f32_e32 v213, v213, v139
	v_mul_f32_e32 v139, v108, v108
	v_fmac_f32_e32 v139, v109, v109
	v_mul_f32_e32 v140, v110, v110
	v_fmac_f32_e32 v140, v111, v111
	v_add_f32_e32 v139, v139, v140
	v_add_f32_e32 v213, v213, v139
	v_mov_b32_e32 v139, v213
	v_mov_b32_e32 v140, v213
	s_nop 1
	v_permlane16_swap_b32_e32 v139, v140
	v_add_f32_e32 v213, v139, v140
	v_mov_b32_e32 v139, v213
	v_mov_b32_e32 v140, v213
	s_nop 1
	v_permlane32_swap_b32_e32 v139, v140
	v_add_f32_e32 v213, v139, v140
	v_mul_f32_e32 v139, v16, v16
	v_fmac_f32_e32 v139, v17, v17
	v_mul_f32_e32 v140, v18, v18
	v_fmac_f32_e32 v140, v19, v19
	v_add_f32_e32 v139, v139, v140
	v_mov_b32_e32 v214, v139
	v_mul_f32_e32 v139, v48, v48
	v_fmac_f32_e32 v139, v49, v49
	v_mul_f32_e32 v140, v50, v50
	v_fmac_f32_e32 v140, v51, v51
	v_add_f32_e32 v139, v139, v140
	v_add_f32_e32 v214, v214, v139
	v_mul_f32_e32 v139, v80, v80
	v_fmac_f32_e32 v139, v81, v81
	v_mul_f32_e32 v140, v82, v82
	v_fmac_f32_e32 v140, v83, v83
	v_add_f32_e32 v139, v139, v140
	v_add_f32_e32 v214, v214, v139
	v_mul_f32_e32 v139, v112, v112
	v_fmac_f32_e32 v139, v113, v113
	v_mul_f32_e32 v140, v114, v114
	v_fmac_f32_e32 v140, v115, v115
	v_add_f32_e32 v139, v139, v140
	v_add_f32_e32 v214, v214, v139
	v_mov_b32_e32 v139, v214
	v_mov_b32_e32 v140, v214
	s_nop 1
	v_permlane16_swap_b32_e32 v139, v140
	v_add_f32_e32 v214, v139, v140
	v_mov_b32_e32 v139, v214
	v_mov_b32_e32 v140, v214
	s_nop 1
	v_permlane32_swap_b32_e32 v139, v140
	v_add_f32_e32 v214, v139, v140
	v_mul_f32_e32 v139, v20, v20
	v_fmac_f32_e32 v139, v21, v21
	v_mul_f32_e32 v140, v22, v22
	v_fmac_f32_e32 v140, v23, v23
	v_add_f32_e32 v139, v139, v140
	v_mov_b32_e32 v215, v139
	v_mul_f32_e32 v139, v52, v52
	v_fmac_f32_e32 v139, v53, v53
	v_mul_f32_e32 v140, v54, v54
	v_fmac_f32_e32 v140, v55, v55
	v_add_f32_e32 v139, v139, v140
	v_add_f32_e32 v215, v215, v139
	v_mul_f32_e32 v139, v84, v84
	v_fmac_f32_e32 v139, v85, v85
	v_mul_f32_e32 v140, v86, v86
	v_fmac_f32_e32 v140, v87, v87
	v_add_f32_e32 v139, v139, v140
	v_add_f32_e32 v215, v215, v139
	v_mul_f32_e32 v139, v116, v116
	v_fmac_f32_e32 v139, v117, v117
	v_mul_f32_e32 v140, v118, v118
	v_fmac_f32_e32 v140, v119, v119
	v_add_f32_e32 v139, v139, v140
	v_add_f32_e32 v215, v215, v139
	v_mov_b32_e32 v139, v215
	v_mov_b32_e32 v140, v215
	s_nop 1
	v_permlane16_swap_b32_e32 v139, v140
	v_add_f32_e32 v215, v139, v140
	v_mov_b32_e32 v139, v215
	v_mov_b32_e32 v140, v215
	s_nop 1
	v_permlane32_swap_b32_e32 v139, v140
	v_add_f32_e32 v215, v139, v140
	v_mul_f32_e32 v139, v24, v24
	v_fmac_f32_e32 v139, v25, v25
	v_mul_f32_e32 v140, v26, v26
	v_fmac_f32_e32 v140, v27, v27
	v_add_f32_e32 v139, v139, v140
	v_mov_b32_e32 v216, v139
	v_mul_f32_e32 v139, v56, v56
	v_fmac_f32_e32 v139, v57, v57
	v_mul_f32_e32 v140, v58, v58
	v_fmac_f32_e32 v140, v59, v59
	v_add_f32_e32 v139, v139, v140
	v_add_f32_e32 v216, v216, v139
	v_mul_f32_e32 v139, v88, v88
	v_fmac_f32_e32 v139, v89, v89
	v_mul_f32_e32 v140, v90, v90
	v_fmac_f32_e32 v140, v91, v91
	v_add_f32_e32 v139, v139, v140
	v_add_f32_e32 v216, v216, v139
	v_mul_f32_e32 v139, v120, v120
	v_fmac_f32_e32 v139, v121, v121
	v_mul_f32_e32 v140, v122, v122
	v_fmac_f32_e32 v140, v123, v123
	v_add_f32_e32 v139, v139, v140
	v_add_f32_e32 v216, v216, v139
	v_mov_b32_e32 v139, v216
	v_mov_b32_e32 v140, v216
	s_nop 1
	v_permlane16_swap_b32_e32 v139, v140
	v_add_f32_e32 v216, v139, v140
	v_mov_b32_e32 v139, v216
	v_mov_b32_e32 v140, v216
	s_nop 1
	v_permlane32_swap_b32_e32 v139, v140
	v_add_f32_e32 v216, v139, v140
	v_mul_f32_e32 v139, v28, v28
	v_fmac_f32_e32 v139, v29, v29
	v_mul_f32_e32 v140, v30, v30
	v_fmac_f32_e32 v140, v31, v31
	v_add_f32_e32 v139, v139, v140
	v_mov_b32_e32 v217, v139
	v_mul_f32_e32 v139, v60, v60
	v_fmac_f32_e32 v139, v61, v61
	v_mul_f32_e32 v140, v62, v62
	v_fmac_f32_e32 v140, v63, v63
	v_add_f32_e32 v139, v139, v140
	v_add_f32_e32 v217, v217, v139
	v_mul_f32_e32 v139, v92, v92
	v_fmac_f32_e32 v139, v93, v93
	v_mul_f32_e32 v140, v94, v94
	v_fmac_f32_e32 v140, v95, v95
	v_add_f32_e32 v139, v139, v140
	v_add_f32_e32 v217, v217, v139
	v_mul_f32_e32 v139, v124, v124
	v_fmac_f32_e32 v139, v125, v125
	v_mul_f32_e32 v140, v126, v126
	v_fmac_f32_e32 v140, v127, v127
	v_add_f32_e32 v139, v139, v140
	v_add_f32_e32 v217, v217, v139
	v_mov_b32_e32 v139, v217
	v_mov_b32_e32 v140, v217
	s_nop 1
	v_permlane16_swap_b32_e32 v139, v140
	v_add_f32_e32 v217, v139, v140
	v_mov_b32_e32 v139, v217
	v_mov_b32_e32 v140, v217
	s_nop 1
	v_permlane32_swap_b32_e32 v139, v140
	v_add_f32_e32 v217, v139, v140
	v_mov_b32_e32 v147, 0
	s_cmpk_ge_i32 s18, 0x100
	s_cbranch_scc1 .Lst0_pkv
	s_lshr_b32 s19, s18, 6
	s_lshl_b32 s19, s19, 2
	v_lshl_add_u32 v146, v142, 4, s19
	v_lshl_add_u64 v[148:149], s[58:59], 0, v[146:147]
	s_movk_i32 s19, 0x100
	s_branch .Lst0_ssqst
.Lst0_pkv:
	s_sub_i32 s19, s18, 0x100
	s_lshr_b32 s19, s19, 6
	s_lshl_b32 s19, s19, 2
	v_lshl_add_u32 v146, v142, 3, s19
	v_lshl_add_u64 v[148:149], s[60:61], 0, v[146:147]
	s_movk_i32 s19, 0x80
.Lst0_ssqst:
	s_mov_b32 s20, s19
	s_mov_b32 s21, 0
	s_and_saveexec_b64 s[12:13], s[14:15]
	global_store_dword v[148:149], v210, off
	v_lshl_add_u64 v[148:149], v[148:149], 0, s[20:21]
	global_store_dword v[148:149], v211, off
	v_lshl_add_u64 v[148:149], v[148:149], 0, s[20:21]
	global_store_dword v[148:149], v212, off
	v_lshl_add_u64 v[148:149], v[148:149], 0, s[20:21]
	global_store_dword v[148:149], v213, off
	v_lshl_add_u64 v[148:149], v[148:149], 0, s[20:21]
	global_store_dword v[148:149], v214, off
	v_lshl_add_u64 v[148:149], v[148:149], 0, s[20:21]
	global_store_dword v[148:149], v215, off
	v_lshl_add_u64 v[148:149], v[148:149], 0, s[20:21]
	global_store_dword v[148:149], v216, off
	v_lshl_add_u64 v[148:149], v[148:149], 0, s[20:21]
	global_store_dword v[148:149], v217, off
	s_or_b64 exec, exec, s[12:13]
.Lst0_nossq:
	s_cmpk_lg_i32 s18, 0x180
	s_cbranch_scc1 .Lst0_nodt
	v_mov_b32_e32 v147, 0
	v_lshlrev_b32_e32 v146, 4, v142
	v_lshl_add_u64 v[148:149], s[46:47], 0, v[146:147]
	s_mov_b64 s[20:21], 0x100
	s_and_saveexec_b64 s[12:13], s[14:15]
	global_store_dwordx4 v[148:149], v[64:67], off
	v_lshl_add_u64 v[148:149], v[148:149], 0, s[20:21]
	global_store_dwordx4 v[148:149], v[68:71], off
	v_lshl_add_u64 v[148:149], v[148:149], 0, s[20:21]
	global_store_dwordx4 v[148:149], v[72:75], off
	v_lshl_add_u64 v[148:149], v[148:149], 0, s[20:21]
	global_store_dwordx4 v[148:149], v[76:79], off
	v_lshl_add_u64 v[148:149], v[148:149], 0, s[20:21]
	global_store_dwordx4 v[148:149], v[80:83], off
	v_lshl_add_u64 v[148:149], v[148:149], 0, s[20:21]
	global_store_dwordx4 v[148:149], v[84:87], off
	v_lshl_add_u64 v[148:149], v[148:149], 0, s[20:21]
	global_store_dwordx4 v[148:149], v[88:91], off
	v_lshl_add_u64 v[148:149], v[148:149], 0, s[20:21]
	global_store_dwordx4 v[148:149], v[92:95], off
	s_or_b64 exec, exec, s[12:13]
.Lst0_nodt:
	v_and_b32_e32 v139, 63, v129
	v_lshrrev_b32_e32 v140, 3, v139
	v_and_b32_e32 v141, 7, v139
	v_lshl_add_u32 v139, v137, 7, v140
	v_add_u32_e32 v139, s10, v139
	s_lshl_b32 s19, s18, 1
	v_lshl_add_u32 v146, v141, 4, s19
	v_mov_b32_e32 v147, 0
	v_lshl_add_u64 v[146:147], s[4:5], 0, v[146:147]
	s_movk_i32 s19, 0xe00
	v_mad_u64_u32 v[144:145], s[20:21], v139, s19, v[146:147]
	s_mov_b64 s[16:17], 0x7000
	s_branch .Lst0_store
.Lst0_mem:
	v_and_b32_e32 v139, 63, v129
	v_lshrrev_b32_e32 v140, 3, v139
	v_and_b32_e32 v141, 7, v139
	v_lshl_add_u32 v139, v137, 7, v140
	v_add_u32_e32 v139, s10, v139
	v_add_u32_e32 v139, 0xffffc000, v139
	s_and_b32 s19, s18, 0x3ff
	s_lshl_b32 s19, s19, 1
	v_lshl_add_u32 v146, v141, 4, s19
	v_mov_b32_e32 v147, 0
	s_cmpk_lt_i32 s18, 0x400
	s_mov_b32 s20, 0x6070000
	s_cselect_b32 s20, 0x5f70000, s20
	s_add_u32 s20, s82, s20
	s_addc_u32 s21, s83, 0
	v_lshl_add_u64 v[146:147], s[20:21], 0, v[146:147]
	v_mov_b32_e32 v149, 0
	v_mov_b32_e32 v148, v139
	v_lshlrev_b64 v[148:149], 11, v[148:149]
	v_lshl_add_u64 v[144:145], v[146:147], 0, v[148:149]
	s_mov_b64 s[16:17], 0x4000
.Lst0_store:
	v_and_b32_e32 v139, 7, v134
	v_lshrrev_b32_e32 v140, 1, v135
	v_and_b32_e32 v141, 1, v135
	v_lshlrev_b32_e32 v146, 7, v134
	v_lshl_add_u32 v146, v136, 13, v146
	v_add_u32_e32 v146, 0x10010, v146
	v_lshl_add_u32 v146, v141, 3, v146
	v_or_b32_e32 v141, 0, v140
	v_xor_b32_e32 v141, v141, v139
	v_lshl_add_u32 v180, v141, 4, v146
	v_or_b32_e32 v141, 2, v140
	v_xor_b32_e32 v141, v141, v139
	v_lshl_add_u32 v181, v141, 4, v146
	v_or_b32_e32 v141, 4, v140
	v_xor_b32_e32 v141, v141, v139
	v_lshl_add_u32 v182, v141, 4, v146
	v_or_b32_e32 v141, 6, v140
	v_xor_b32_e32 v141, v141, v139
	v_lshl_add_u32 v183, v141, 4, v146
	v_and_b32_e32 v139, 63, v129
	v_lshrrev_b32_e32 v140, 3, v139
	v_and_b32_e32 v141, 7, v139
	v_xor_b32_e32 v143, v140, v141
	v_lshlrev_b32_e32 v143, 4, v143
	v_lshl_add_u32 v143, v140, 7, v143
	v_lshl_add_u32 v143, v136, 13, v143
	v_add_u32_e32 v143, 0x10010, v143
	v_cvt_pk_bf16_f32 v0, v0, v1
	v_cvt_pk_bf16_f32 v1, v2, v3
	ds_write_b64 v180, v[0:1]
	v_cvt_pk_bf16_f32 v32, v32, v33
	v_cvt_pk_bf16_f32 v33, v34, v35
	ds_write_b64 v181, v[32:33]
	v_cvt_pk_bf16_f32 v64, v64, v65
	v_cvt_pk_bf16_f32 v65, v66, v67
	ds_write_b64 v182, v[64:65]
	v_cvt_pk_bf16_f32 v96, v96, v97
	v_cvt_pk_bf16_f32 v97, v98, v99
	ds_write_b64 v183, v[96:97]
	v_cvt_pk_bf16_f32 v4, v4, v5
	v_cvt_pk_bf16_f32 v5, v6, v7
	ds_write_b64 v180, v[4:5] offset:2048
	v_cvt_pk_bf16_f32 v36, v36, v37
	v_cvt_pk_bf16_f32 v37, v38, v39
	ds_write_b64 v181, v[36:37] offset:2048
	v_cvt_pk_bf16_f32 v68, v68, v69
	v_cvt_pk_bf16_f32 v69, v70, v71
	ds_write_b64 v182, v[68:69] offset:2048
	v_cvt_pk_bf16_f32 v100, v100, v101
	v_cvt_pk_bf16_f32 v101, v102, v103
	ds_write_b64 v183, v[100:101] offset:2048
	v_cvt_pk_bf16_f32 v8, v8, v9
	v_cvt_pk_bf16_f32 v9, v10, v11
	ds_write_b64 v180, v[8:9] offset:4096
	v_cvt_pk_bf16_f32 v40, v40, v41
	v_cvt_pk_bf16_f32 v41, v42, v43
	ds_write_b64 v181, v[40:41] offset:4096
	v_cvt_pk_bf16_f32 v72, v72, v73
	v_cvt_pk_bf16_f32 v73, v74, v75
	ds_write_b64 v182, v[72:73] offset:4096
	v_cvt_pk_bf16_f32 v104, v104, v105
	v_cvt_pk_bf16_f32 v105, v106, v107
	ds_write_b64 v183, v[104:105] offset:4096
	v_cvt_pk_bf16_f32 v12, v12, v13
	v_cvt_pk_bf16_f32 v13, v14, v15
	ds_write_b64 v180, v[12:13] offset:6144
	v_cvt_pk_bf16_f32 v44, v44, v45
	v_cvt_pk_bf16_f32 v45, v46, v47
	ds_write_b64 v181, v[44:45] offset:6144
	v_cvt_pk_bf16_f32 v76, v76, v77
	v_cvt_pk_bf16_f32 v77, v78, v79
	ds_write_b64 v182, v[76:77] offset:6144
	v_cvt_pk_bf16_f32 v108, v108, v109
	v_cvt_pk_bf16_f32 v109, v110, v111
	ds_write_b64 v183, v[108:109] offset:6144
	s_waitcnt lgkmcnt(0)
	ds_read_b128 v[0:3], v143
	ds_read_b128 v[4:7], v143 offset:1024
	ds_read_b128 v[8:11], v143 offset:2048
	ds_read_b128 v[12:15], v143 offset:3072
	ds_read_b128 v[32:35], v143 offset:4096
	ds_read_b128 v[36:39], v143 offset:5120
	ds_read_b128 v[40:43], v143 offset:6144
	ds_read_b128 v[44:47], v143 offset:7168
	s_waitcnt lgkmcnt(7)
	global_store_dwordx4 v[144:145], v[0:3], off
	v_lshl_add_u64 v[144:145], v[144:145], 0, s[16:17]
	s_waitcnt lgkmcnt(6)
	global_store_dwordx4 v[144:145], v[4:7], off
	v_lshl_add_u64 v[144:145], v[144:145], 0, s[16:17]
	s_waitcnt lgkmcnt(5)
	global_store_dwordx4 v[144:145], v[8:11], off
	v_lshl_add_u64 v[144:145], v[144:145], 0, s[16:17]
	s_waitcnt lgkmcnt(4)
	global_store_dwordx4 v[144:145], v[12:15], off
	v_lshl_add_u64 v[144:145], v[144:145], 0, s[16:17]
	s_waitcnt lgkmcnt(3)
	global_store_dwordx4 v[144:145], v[32:35], off
	v_lshl_add_u64 v[144:145], v[144:145], 0, s[16:17]
	s_waitcnt lgkmcnt(2)
	global_store_dwordx4 v[144:145], v[36:39], off
	v_lshl_add_u64 v[144:145], v[144:145], 0, s[16:17]
	s_waitcnt lgkmcnt(1)
	global_store_dwordx4 v[144:145], v[40:43], off
	v_lshl_add_u64 v[144:145], v[144:145], 0, s[16:17]
	s_waitcnt lgkmcnt(0)
	global_store_dwordx4 v[144:145], v[44:47], off
	v_lshl_add_u64 v[144:145], v[144:145], 0, s[16:17]
	v_cvt_pk_bf16_f32 v16, v16, v17
	v_cvt_pk_bf16_f32 v17, v18, v19
	ds_write_b64 v180, v[16:17]
	v_cvt_pk_bf16_f32 v48, v48, v49
	v_cvt_pk_bf16_f32 v49, v50, v51
	ds_write_b64 v181, v[48:49]
	v_cvt_pk_bf16_f32 v80, v80, v81
	v_cvt_pk_bf16_f32 v81, v82, v83
	ds_write_b64 v182, v[80:81]
	v_cvt_pk_bf16_f32 v112, v112, v113
	v_cvt_pk_bf16_f32 v113, v114, v115
	ds_write_b64 v183, v[112:113]
	v_cvt_pk_bf16_f32 v20, v20, v21
	v_cvt_pk_bf16_f32 v21, v22, v23
	ds_write_b64 v180, v[20:21] offset:2048
	v_cvt_pk_bf16_f32 v52, v52, v53
	v_cvt_pk_bf16_f32 v53, v54, v55
	ds_write_b64 v181, v[52:53] offset:2048
	v_cvt_pk_bf16_f32 v84, v84, v85
	v_cvt_pk_bf16_f32 v85, v86, v87
	ds_write_b64 v182, v[84:85] offset:2048
	v_cvt_pk_bf16_f32 v116, v116, v117
	v_cvt_pk_bf16_f32 v117, v118, v119
	ds_write_b64 v183, v[116:117] offset:2048
	v_cvt_pk_bf16_f32 v24, v24, v25
	v_cvt_pk_bf16_f32 v25, v26, v27
	ds_write_b64 v180, v[24:25] offset:4096
	v_cvt_pk_bf16_f32 v56, v56, v57
	v_cvt_pk_bf16_f32 v57, v58, v59
	ds_write_b64 v181, v[56:57] offset:4096
	v_cvt_pk_bf16_f32 v88, v88, v89
	v_cvt_pk_bf16_f32 v89, v90, v91
	ds_write_b64 v182, v[88:89] offset:4096
	v_cvt_pk_bf16_f32 v120, v120, v121
	v_cvt_pk_bf16_f32 v121, v122, v123
	ds_write_b64 v183, v[120:121] offset:4096
	v_cvt_pk_bf16_f32 v28, v28, v29
	v_cvt_pk_bf16_f32 v29, v30, v31
	ds_write_b64 v180, v[28:29] offset:6144
	v_cvt_pk_bf16_f32 v60, v60, v61
	v_cvt_pk_bf16_f32 v61, v62, v63
	ds_write_b64 v181, v[60:61] offset:6144
	v_cvt_pk_bf16_f32 v92, v92, v93
	v_cvt_pk_bf16_f32 v93, v94, v95
	ds_write_b64 v182, v[92:93] offset:6144
	v_cvt_pk_bf16_f32 v124, v124, v125
	v_cvt_pk_bf16_f32 v125, v126, v127
	ds_write_b64 v183, v[124:125] offset:6144
	s_waitcnt lgkmcnt(0)
	ds_read_b128 v[16:19], v143
	ds_read_b128 v[20:23], v143 offset:1024
	ds_read_b128 v[24:27], v143 offset:2048
	ds_read_b128 v[28:31], v143 offset:3072
	ds_read_b128 v[48:51], v143 offset:4096
	ds_read_b128 v[52:55], v143 offset:5120
	ds_read_b128 v[56:59], v143 offset:6144
	ds_read_b128 v[60:63], v143 offset:7168
	s_waitcnt lgkmcnt(7)
	global_store_dwordx4 v[144:145], v[16:19], off
	v_lshl_add_u64 v[144:145], v[144:145], 0, s[16:17]
	s_waitcnt lgkmcnt(6)
	global_store_dwordx4 v[144:145], v[20:23], off
	v_lshl_add_u64 v[144:145], v[144:145], 0, s[16:17]
	s_waitcnt lgkmcnt(5)
	global_store_dwordx4 v[144:145], v[24:27], off
	v_lshl_add_u64 v[144:145], v[144:145], 0, s[16:17]
	s_waitcnt lgkmcnt(4)
	global_store_dwordx4 v[144:145], v[28:31], off
	v_lshl_add_u64 v[144:145], v[144:145], 0, s[16:17]
	s_waitcnt lgkmcnt(3)
	global_store_dwordx4 v[144:145], v[48:51], off
	v_lshl_add_u64 v[144:145], v[144:145], 0, s[16:17]
	s_waitcnt lgkmcnt(2)
	global_store_dwordx4 v[144:145], v[52:55], off
	v_lshl_add_u64 v[144:145], v[144:145], 0, s[16:17]
	s_waitcnt lgkmcnt(1)
	global_store_dwordx4 v[144:145], v[56:59], off
	v_lshl_add_u64 v[144:145], v[144:145], 0, s[16:17]
	s_waitcnt lgkmcnt(0)
	global_store_dwordx4 v[144:145], v[60:63], off
	v_lshl_add_u64 v[144:145], v[144:145], 0, s[16:17]
	s_branch .Lst0_fin
